# merged s_waitcnt pairs in the attention main loop (one wait per two PV MFMAs, one K wait per half-step)
# speedup vs baseline: 1.0104x; 1.0004x over previous
; #define LAS __attribute__((address_space(3)))
; #define MFMA32(a, b, c) __builtin_amdgcn_mfma_f32_32x32x16_bf16((a), (b), (c), 0, 0, 0)
; __device__ __forceinline__ s16x4 vtr(LAS const unsigned char* p) { return __builtin_bit_cast(s16x4, __builtin_amdgcn_ds_read_tr16_b64_v4i16((LAS v4i16_t*)p)); }
; template <bool TAIL> ...
;     ...
; #pragma unroll
;     for (int ks = 0; ks < 4; ++ks) {
;         const bf16x8 a0 = *(LAS const bf16x8*)(Kn + ka + (((2 * ks + hi) ^ kx) << 4));
;         Sn = MFMA32(a0, qf[ks], Sn);
;     }
;     float ls = 0.f;
; #pragma unroll
;     for (int i = 0; i < 16; ++i) { Sc[i] = __builtin_amdgcn_exp2f(Sc[i]); ls += Sc[i]; }
;     l_run += ls;
; #pragma unroll
;     for (int kk = 0; kk < 2; ++kk) {
;         if (kk == 1) __builtin_amdgcn_sched_barrier(0);
;         const bf16x8 pb = pack8(Sc, kk);
; #pragma unroll
;         for (int d = 0; d < 4; ++d) {
;             LAS const unsigned char* p = Vc + va + kk * 4096 + (((2 * d + blk) ^ vx) << 5);
;             const s16x4 lo = vtr(p), hi4 = vtr(p + 2048);
;             const bf16x8 a = __builtin_shufflevector(lo, hi4, 0, 1, 2, 3, 4, 5, 6, 7);
;             O[d] = MFMA32(a, pb, O[d]);
;         }
;     }
.Lda_h1_body:
	ds_read_b64_tr_b16 v[136:137], v156 offset:49152
	ds_read_b64_tr_b16 v[138:139], v156 offset:51200
	v_exp_f32_e32 v64, v64
	v_exp_f32_e32 v65, v65
	v_exp_f32_e32 v66, v66
	v_mfma_f32_32x32x16_bf16 v[80:95], v[240:243], v[168:171], v[120:135]
	ds_read_b64_tr_b16 v[140:141], v157 offset:49152
	ds_read_b64_tr_b16 v[142:143], v157 offset:51200
	ds_read_b64_tr_b16 v[144:145], v158 offset:49152
	ds_read_b64_tr_b16 v[146:147], v158 offset:51200
	v_exp_f32_e32 v67, v67
	v_exp_f32_e32 v68, v68
	v_exp_f32_e32 v69, v69
	v_add_f32_e32 v188, v64, v65
	v_mfma_f32_32x32x16_bf16 v[80:95], v[244:247], v[172:175], v[80:95]
	ds_read_b64_tr_b16 v[148:149], v159 offset:49152
	ds_read_b64_tr_b16 v[150:151], v159 offset:51200
	ds_read_b64_tr_b16 v[96:97], v156 offset:53248
	ds_read_b64_tr_b16 v[98:99], v156 offset:55296
	v_exp_f32_e32 v70, v70
	v_exp_f32_e32 v71, v71
	v_cvt_pk_bf16_f32 v196, v64, v65
	v_add_f32_e32 v188, v188, v66
	v_cvt_pk_bf16_f32 v197, v66, v67
	v_add_f32_e32 v188, v188, v67
	v_mfma_f32_32x32x16_bf16 v[80:95], v[248:251], v[176:179], v[80:95]
	ds_read_b64_tr_b16 v[100:101], v157 offset:53248
	ds_read_b64_tr_b16 v[102:103], v157 offset:55296
	ds_read_b64_tr_b16 v[104:105], v158 offset:53248
	ds_read_b64_tr_b16 v[106:107], v158 offset:55296
	v_exp_f32_e32 v72, v72
	v_exp_f32_e32 v73, v73
	v_exp_f32_e32 v74, v74
	v_cvt_pk_bf16_f32 v198, v68, v69
	v_add_f32_e32 v188, v188, v68
	v_add_f32_e32 v188, v188, v69
	v_mfma_f32_32x32x16_bf16 v[80:95], v[204:207], v[180:183], v[80:95]
	ds_read_b64_tr_b16 v[108:109], v159 offset:53248
	s_waitcnt lgkmcnt(14)
	ds_read_b64_tr_b16 v[110:111], v159 offset:55296
	v_cvt_pk_bf16_f32 v199, v70, v71
	v_exp_f32_e32 v75, v75
	v_exp_f32_e32 v76, v76
	v_exp_f32_e32 v77, v77
	v_add_f32_e32 v188, v188, v70
	v_add_f32_e32 v188, v188, v71
	s_waitcnt lgkmcnt(12)
	v_mfma_f32_32x32x16_bf16 v[48:63], v[136:139], v[196:199], v[48:63]
	ds_read_b128 v[240:243], v152 offset:8192
	v_exp_f32_e32 v78, v78
	v_exp_f32_e32 v79, v79
	v_cvt_pk_bf16_f32 v200, v72, v73
	v_add_f32_e32 v189, v72, v73
	v_cvt_pk_bf16_f32 v201, v74, v75
	v_add_f32_e32 v189, v189, v74
	v_mfma_f32_32x32x16_bf16 v[32:47], v[140:143], v[196:199], v[32:47]
	ds_read_b128 v[244:247], v153 offset:8192
	v_cvt_pk_bf16_f32 v202, v76, v77
	v_add_f32_e32 v189, v189, v75
	v_add_f32_e32 v189, v189, v76
	v_cvt_pk_bf16_f32 v203, v78, v79
	v_add_f32_e32 v189, v189, v77
	s_waitcnt lgkmcnt(10)
	v_mfma_f32_32x32x16_bf16 v[16:31], v[144:147], v[196:199], v[16:31]
	ds_read_b128 v[248:251], v154 offset:8192
	v_add_f32_e32 v189, v189, v78
	v_add_f32_e32 v165, v165, v188
	v_add_f32_e32 v189, v189, v79
	v_mfma_f32_32x32x16_bf16 v[0:15], v[148:151], v[196:199], v[0:15]
	ds_read_b128 v[204:207], v155 offset:8192
	v_add_f32_e32 v165, v165, v189
	v_max3_f32 v166, v80, v81, v82
	v_max3_f32 v166, v166, v83, v84
	s_waitcnt lgkmcnt(8)
	v_mfma_f32_32x32x16_bf16 v[48:63], v[96:99], v[200:203], v[48:63]
	v_max3_f32 v166, v166, v85, v86
	v_max3_f32 v166, v166, v87, v88
	v_max3_f32 v166, v166, v89, v90
	v_mfma_f32_32x32x16_bf16 v[32:47], v[100:103], v[200:203], v[32:47]
	v_max3_f32 v166, v166, v91, v92
	v_max3_f32 v166, v166, v93, v94
	v_max_f32_e32 v166, v166, v95
	v_cmp_lt_f32_e32 vcc, s92, v166
	s_xor_b32 s14, s20, 0x8000
	s_add_i32 s14, s14, s23
	s_mov_b32 s15, m0
	s_add_i32 m0, s14, 0xc000
	s_nop 0
	global_load_lds_dwordx4 v211, s[12:13]
	s_add_i32 m0, s14, 0xe000
	s_add_u32 s4, s12, 0x60000
	s_addc_u32 s5, s13, 0
	s_waitcnt lgkmcnt(4)
	v_mfma_f32_32x32x16_bf16 v[16:31], v[104:107], v[200:203], v[16:31]
	global_load_lds_dwordx4 v211, s[4:5]
	s_mov_b32 m0, s15
	v_mfma_f32_32x32x16_bf16 v[0:15], v[108:111], v[200:203], v[0:15]
	s_cbranch_vccnz .Lda_h1_resc
.Lda_h1_done:
	ds_read_b64_tr_b16 v[136:137], v156 offset:57344
	ds_read_b64_tr_b16 v[138:139], v156 offset:59392
	v_exp_f32_e32 v80, v80
	v_exp_f32_e32 v81, v81
	v_exp_f32_e32 v82, v82
	s_waitcnt lgkmcnt(2)
	v_mfma_f32_32x32x16_bf16 v[64:79], v[240:243], v[168:171], v[120:135]
	ds_read_b64_tr_b16 v[140:141], v157 offset:57344
	ds_read_b64_tr_b16 v[142:143], v157 offset:59392
	ds_read_b64_tr_b16 v[144:145], v158 offset:57344
	ds_read_b64_tr_b16 v[146:147], v158 offset:59392
	v_exp_f32_e32 v83, v83
	v_exp_f32_e32 v84, v84
	v_exp_f32_e32 v85, v85
	v_add_f32_e32 v188, v80, v81
	v_mfma_f32_32x32x16_bf16 v[64:79], v[244:247], v[172:175], v[64:79]
	ds_read_b64_tr_b16 v[148:149], v159 offset:57344
	ds_read_b64_tr_b16 v[150:151], v159 offset:59392
	ds_read_b64_tr_b16 v[96:97], v156 offset:61440
	ds_read_b64_tr_b16 v[98:99], v156 offset:63488
	v_exp_f32_e32 v86, v86
	v_exp_f32_e32 v87, v87
	v_cvt_pk_bf16_f32 v196, v80, v81
	v_add_f32_e32 v188, v188, v82
	v_cvt_pk_bf16_f32 v197, v82, v83
	v_add_f32_e32 v188, v188, v83
	v_mfma_f32_32x32x16_bf16 v[64:79], v[248:251], v[176:179], v[64:79]
	ds_read_b64_tr_b16 v[100:101], v157 offset:61440
	ds_read_b64_tr_b16 v[102:103], v157 offset:63488
	ds_read_b64_tr_b16 v[104:105], v158 offset:61440
	ds_read_b64_tr_b16 v[106:107], v158 offset:63488
	v_exp_f32_e32 v88, v88
	v_exp_f32_e32 v89, v89
	v_exp_f32_e32 v90, v90
	v_cvt_pk_bf16_f32 v198, v84, v85
	v_add_f32_e32 v188, v188, v84
	v_add_f32_e32 v188, v188, v85
	v_mfma_f32_32x32x16_bf16 v[64:79], v[204:207], v[180:183], v[64:79]
	ds_read_b64_tr_b16 v[108:109], v159 offset:61440
	s_waitcnt lgkmcnt(14)
	ds_read_b64_tr_b16 v[110:111], v159 offset:63488
	v_cvt_pk_bf16_f32 v199, v86, v87
	v_exp_f32_e32 v91, v91
	v_exp_f32_e32 v92, v92
	v_exp_f32_e32 v93, v93
	v_add_f32_e32 v188, v188, v86
	v_add_f32_e32 v188, v188, v87
	s_waitcnt lgkmcnt(12)
; #define LAS __attribute__((address_space(3)))
; #define MFMA32(a, b, c) __builtin_amdgcn_mfma_f32_32x32x16_bf16((a), (b), (c), 0, 0, 0)
; __device__ __forceinline__ s16x4 vtr(LAS const unsigned char* p) { return __builtin_bit_cast(s16x4, __builtin_amdgcn_ds_read_tr16_b64_v4i16((LAS v4i16_t*)p)); }
; template <bool TAIL> ...
;     ...
; #pragma unroll
;     for (int ks = 0; ks < 4; ++ks) {
;         const bf16x8 a0 = *(LAS const bf16x8*)(Kn + ka + (((2 * ks + hi) ^ kx) << 4));
;         Sn = MFMA32(a0, qf[ks], Sn);
;     }
;     float ls = 0.f;
; #pragma unroll
;     for (int i = 0; i < 16; ++i) { Sc[i] = __builtin_amdgcn_exp2f(Sc[i]); ls += Sc[i]; }
;     l_run += ls;
; #pragma unroll
;     for (int kk = 0; kk < 2; ++kk) {
;         if (kk == 1) __builtin_amdgcn_sched_barrier(0);
;         const bf16x8 pb = pack8(Sc, kk);
; #pragma unroll
;         for (int d = 0; d < 4; ++d) {
;             LAS const unsigned char* p = Vc + va + kk * 4096 + (((2 * d + blk) ^ vx) << 5);
;             const s16x4 lo = vtr(p), hi4 = vtr(p + 2048);
;             const bf16x8 a = __builtin_shufflevector(lo, hi4, 0, 1, 2, 3, 4, 5, 6, 7);
;             O[d] = MFMA32(a, pb, O[d]);
;         }
;     }
	v_mfma_f32_32x32x16_bf16 v[48:63], v[136:139], v[196:199], v[48:63]
	ds_read_b128 v[240:243], v152 offset:12288
	v_exp_f32_e32 v94, v94
	v_exp_f32_e32 v95, v95
	v_cvt_pk_bf16_f32 v200, v88, v89
	v_add_f32_e32 v189, v88, v89
	v_cvt_pk_bf16_f32 v201, v90, v91
	v_add_f32_e32 v189, v189, v90
	v_mfma_f32_32x32x16_bf16 v[32:47], v[140:143], v[196:199], v[32:47]
	ds_read_b128 v[244:247], v153 offset:12288
	v_cvt_pk_bf16_f32 v202, v92, v93
	v_add_f32_e32 v189, v189, v91
	v_add_f32_e32 v189, v189, v92
	v_cvt_pk_bf16_f32 v203, v94, v95
	v_add_f32_e32 v189, v189, v93
	s_waitcnt lgkmcnt(10)
	v_mfma_f32_32x32x16_bf16 v[16:31], v[144:147], v[196:199], v[16:31]
	ds_read_b128 v[248:251], v154 offset:12288
	v_add_f32_e32 v189, v189, v94
	v_add_f32_e32 v165, v165, v188
	v_add_f32_e32 v189, v189, v95
	v_mfma_f32_32x32x16_bf16 v[0:15], v[148:151], v[196:199], v[0:15]
	ds_read_b128 v[204:207], v155 offset:12288
	v_add3_u32 v152, s16, v224, v225
	v_add3_u32 v153, s16, v224, v226
	v_add3_u32 v154, s16, v224, v227
	v_add3_u32 v155, s16, v224, v228
	v_add_u32_e32 v156, 0x8000, v156
	v_add_u32_e32 v157, 0x8000, v157
	v_add_u32_e32 v158, 0x8000, v158
	v_add_u32_e32 v159, 0x8000, v159
	v_add_f32_e32 v165, v165, v189
	v_max3_f32 v166, v64, v65, v66
	v_max3_f32 v166, v166, v67, v68
	s_waitcnt lgkmcnt(8)
	v_mfma_f32_32x32x16_bf16 v[48:63], v[96:99], v[200:203], v[48:63]
	v_max3_f32 v166, v166, v69, v70
	v_max3_f32 v166, v166, v71, v72
	v_max3_f32 v166, v166, v73, v74
	v_mfma_f32_32x32x16_bf16 v[32:47], v[100:103], v[200:203], v[32:47]
	v_max3_f32 v166, v166, v75, v76
	v_max3_f32 v166, v166, v77, v78
	v_max_f32_e32 v166, v166, v79
	v_cmp_lt_f32_e32 vcc, s92, v166
	s_xor_b32 s14, s20, 0x8000
	s_add_i32 s14, s14, s23
	s_mov_b32 s15, m0
	s_add_i32 m0, s14, 0x10000
	s_add_u32 s4, s12, 0xc0000
	s_addc_u32 s5, s13, 0
	global_load_lds_dwordx4 v211, s[4:5]
	s_add_i32 m0, s14, 0x12000
	s_add_u32 s4, s12, 0x120000
	s_addc_u32 s5, s13, 0
	s_waitcnt lgkmcnt(4)
	v_mfma_f32_32x32x16_bf16 v[16:31], v[104:107], v[200:203], v[16:31]
	global_load_lds_dwordx4 v211, s[4:5]
	s_mov_b32 m0, s15
	v_mfma_f32_32x32x16_bf16 v[0:15], v[108:111], v[200:203], v[0:15]
	s_cbranch_vccnz .Lda_h2_resc
.Lda_h2_done:
	ds_read_b64_tr_b16 v[136:137], v156 offset:32768
	ds_read_b64_tr_b16 v[138:139], v156 offset:34816
	v_exp_f32_e32 v64, v64
	v_exp_f32_e32 v65, v65
	v_exp_f32_e32 v66, v66
	s_waitcnt lgkmcnt(2)
	v_mfma_f32_32x32x16_bf16 v[80:95], v[240:243], v[168:171], v[120:135]
	ds_read_b64_tr_b16 v[140:141], v157 offset:32768
	ds_read_b64_tr_b16 v[142:143], v157 offset:34816
	ds_read_b64_tr_b16 v[144:145], v158 offset:32768
	ds_read_b64_tr_b16 v[146:147], v158 offset:34816
	v_exp_f32_e32 v67, v67
	v_exp_f32_e32 v68, v68
	v_exp_f32_e32 v69, v69
	v_add_f32_e32 v188, v64, v65
	v_mfma_f32_32x32x16_bf16 v[80:95], v[244:247], v[172:175], v[80:95]
	ds_read_b64_tr_b16 v[148:149], v159 offset:32768
	ds_read_b64_tr_b16 v[150:151], v159 offset:34816
	ds_read_b64_tr_b16 v[96:97], v156 offset:36864
	ds_read_b64_tr_b16 v[98:99], v156 offset:38912
	v_exp_f32_e32 v70, v70
	v_exp_f32_e32 v71, v71
	v_cvt_pk_bf16_f32 v196, v64, v65
	v_add_f32_e32 v188, v188, v66
	v_cvt_pk_bf16_f32 v197, v66, v67
	v_add_f32_e32 v188, v188, v67
	v_mfma_f32_32x32x16_bf16 v[80:95], v[248:251], v[176:179], v[80:95]
	ds_read_b64_tr_b16 v[100:101], v157 offset:36864
	ds_read_b64_tr_b16 v[102:103], v157 offset:38912
	ds_read_b64_tr_b16 v[104:105], v158 offset:36864
	ds_read_b64_tr_b16 v[106:107], v158 offset:38912
	v_exp_f32_e32 v72, v72
	v_exp_f32_e32 v73, v73
	v_exp_f32_e32 v74, v74
	v_cvt_pk_bf16_f32 v198, v68, v69
	v_add_f32_e32 v188, v188, v68
	v_add_f32_e32 v188, v188, v69
	v_mfma_f32_32x32x16_bf16 v[80:95], v[204:207], v[180:183], v[80:95]
	ds_read_b64_tr_b16 v[108:109], v159 offset:36864
	s_waitcnt lgkmcnt(14)
	ds_read_b64_tr_b16 v[110:111], v159 offset:38912
	v_cvt_pk_bf16_f32 v199, v70, v71
	v_exp_f32_e32 v75, v75
	v_exp_f32_e32 v76, v76
	v_exp_f32_e32 v77, v77
	v_add_f32_e32 v188, v188, v70
	v_add_f32_e32 v188, v188, v71
	s_waitcnt lgkmcnt(12)
	v_mfma_f32_32x32x16_bf16 v[48:63], v[136:139], v[196:199], v[48:63]
	ds_read_b128 v[240:243], v152
	v_exp_f32_e32 v78, v78
	v_exp_f32_e32 v79, v79
	v_cvt_pk_bf16_f32 v200, v72, v73
	v_add_f32_e32 v189, v72, v73
	v_cvt_pk_bf16_f32 v201, v74, v75
	v_add_f32_e32 v189, v189, v74
	v_mfma_f32_32x32x16_bf16 v[32:47], v[140:143], v[196:199], v[32:47]
	ds_read_b128 v[244:247], v153
	v_cvt_pk_bf16_f32 v202, v76, v77
	v_add_f32_e32 v189, v189, v75
	v_add_f32_e32 v189, v189, v76
	v_cvt_pk_bf16_f32 v203, v78, v79
	v_add_f32_e32 v189, v189, v77
	s_waitcnt lgkmcnt(10)
	v_mfma_f32_32x32x16_bf16 v[16:31], v[144:147], v[196:199], v[16:31]
	ds_read_b128 v[248:251], v154
	v_add_f32_e32 v189, v189, v78
	v_add_f32_e32 v165, v165, v188
	v_add_f32_e32 v189, v189, v79
	v_mfma_f32_32x32x16_bf16 v[0:15], v[148:151], v[196:199], v[0:15]
	ds_read_b128 v[204:207], v155
	v_add_f32_e32 v165, v165, v189
	v_max3_f32 v166, v80, v81, v82
	v_max3_f32 v166, v166, v83, v84
	s_waitcnt lgkmcnt(8)
	v_mfma_f32_32x32x16_bf16 v[48:63], v[96:99], v[200:203], v[48:63]
	v_max3_f32 v166, v166, v85, v86
	v_max3_f32 v166, v166, v87, v88
	v_max3_f32 v166, v166, v89, v90
	v_mfma_f32_32x32x16_bf16 v[32:47], v[100:103], v[200:203], v[32:47]
	v_max3_f32 v166, v166, v91, v92
	v_max3_f32 v166, v166, v93, v94
	v_max_f32_e32 v166, v166, v95
	v_cmp_lt_f32_e32 vcc, s92, v166
	s_waitcnt lgkmcnt(4)
	v_mfma_f32_32x32x16_bf16 v[16:31], v[104:107], v[200:203], v[16:31]
	v_mfma_f32_32x32x16_bf16 v[0:15], v[108:111], v[200:203], v[0:15]
	s_cbranch_vccnz .Lda_h3_resc
; #define LAS __attribute__((address_space(3)))
; #define MFMA32(a, b, c) __builtin_amdgcn_mfma_f32_32x32x16_bf16((a), (b), (c), 0, 0, 0)
; __device__ __forceinline__ s16x4 vtr(LAS const unsigned char* p) { return __builtin_bit_cast(s16x4, __builtin_amdgcn_ds_read_tr16_b64_v4i16((LAS v4i16_t*)p)); }
; template <bool TAIL> ...
;     ...
; #pragma unroll
;     for (int ks = 0; ks < 4; ++ks) {
;         const bf16x8 a0 = *(LAS const bf16x8*)(Kn + ka + (((2 * ks + hi) ^ kx) << 4));
;         Sn = MFMA32(a0, qf[ks], Sn);
;     }
;     float ls = 0.f;
; #pragma unroll
;     for (int i = 0; i < 16; ++i) { Sc[i] = __builtin_amdgcn_exp2f(Sc[i]); ls += Sc[i]; }
;     l_run += ls;
; #pragma unroll
;     for (int kk = 0; kk < 2; ++kk) {
;         if (kk == 1) __builtin_amdgcn_sched_barrier(0);
;         const bf16x8 pb = pack8(Sc, kk);
; #pragma unroll
;         for (int d = 0; d < 4; ++d) {
;             LAS const unsigned char* p = Vc + va + kk * 4096 + (((2 * d + blk) ^ vx) << 5);
;             const s16x4 lo = vtr(p), hi4 = vtr(p + 2048);
;             const bf16x8 a = __builtin_shufflevector(lo, hi4, 0, 1, 2, 3, 4, 5, 6, 7);
;             O[d] = MFMA32(a, pb, O[d]);
;         }
;     }
.Lda_h3_done:
	ds_read_b64_tr_b16 v[136:137], v156 offset:40960
	ds_read_b64_tr_b16 v[138:139], v156 offset:43008
	v_exp_f32_e32 v80, v80
	v_exp_f32_e32 v81, v81
	v_exp_f32_e32 v82, v82
	s_waitcnt lgkmcnt(2)
	v_mfma_f32_32x32x16_bf16 v[64:79], v[240:243], v[168:171], v[120:135]
	ds_read_b64_tr_b16 v[140:141], v157 offset:40960
	ds_read_b64_tr_b16 v[142:143], v157 offset:43008
	ds_read_b64_tr_b16 v[144:145], v158 offset:40960
	ds_read_b64_tr_b16 v[146:147], v158 offset:43008
	v_exp_f32_e32 v83, v83
	v_exp_f32_e32 v84, v84
	v_exp_f32_e32 v85, v85
	v_add_f32_e32 v188, v80, v81
	v_mfma_f32_32x32x16_bf16 v[64:79], v[244:247], v[172:175], v[64:79]
	ds_read_b64_tr_b16 v[148:149], v159 offset:40960
	ds_read_b64_tr_b16 v[150:151], v159 offset:43008
	ds_read_b64_tr_b16 v[96:97], v156 offset:45056
	ds_read_b64_tr_b16 v[98:99], v156 offset:47104
	v_exp_f32_e32 v86, v86
	v_exp_f32_e32 v87, v87
	v_cvt_pk_bf16_f32 v196, v80, v81
	v_add_f32_e32 v188, v188, v82
	v_cvt_pk_bf16_f32 v197, v82, v83
	v_add_f32_e32 v188, v188, v83
	v_mfma_f32_32x32x16_bf16 v[64:79], v[248:251], v[176:179], v[64:79]
	ds_read_b64_tr_b16 v[100:101], v157 offset:45056
	ds_read_b64_tr_b16 v[102:103], v157 offset:47104
	ds_read_b64_tr_b16 v[104:105], v158 offset:45056
	ds_read_b64_tr_b16 v[106:107], v158 offset:47104
	v_exp_f32_e32 v88, v88
	v_exp_f32_e32 v89, v89
	v_exp_f32_e32 v90, v90
	v_cvt_pk_bf16_f32 v198, v84, v85
	v_add_f32_e32 v188, v188, v84
	v_add_f32_e32 v188, v188, v85
	v_mfma_f32_32x32x16_bf16 v[64:79], v[204:207], v[180:183], v[64:79]
	ds_read_b64_tr_b16 v[108:109], v159 offset:45056
	s_waitcnt lgkmcnt(14)
	ds_read_b64_tr_b16 v[110:111], v159 offset:47104
	v_cvt_pk_bf16_f32 v199, v86, v87
	v_exp_f32_e32 v91, v91
	v_exp_f32_e32 v92, v92
	v_exp_f32_e32 v93, v93
	v_add_f32_e32 v188, v188, v86
	v_add_f32_e32 v188, v188, v87
	s_waitcnt lgkmcnt(12)
	v_mfma_f32_32x32x16_bf16 v[48:63], v[136:139], v[196:199], v[48:63]
	ds_read_b128 v[240:243], v152 offset:4096
	v_exp_f32_e32 v94, v94
	v_exp_f32_e32 v95, v95
	v_cvt_pk_bf16_f32 v200, v88, v89
	v_add_f32_e32 v189, v88, v89
	v_cvt_pk_bf16_f32 v201, v90, v91
	v_add_f32_e32 v189, v189, v90
	v_mfma_f32_32x32x16_bf16 v[32:47], v[140:143], v[196:199], v[32:47]
	ds_read_b128 v[244:247], v153 offset:4096
	v_cvt_pk_bf16_f32 v202, v92, v93
	v_add_f32_e32 v189, v189, v91
	v_add_f32_e32 v189, v189, v92
	v_cvt_pk_bf16_f32 v203, v94, v95
	v_add_f32_e32 v189, v189, v93
	s_waitcnt lgkmcnt(10)
	v_mfma_f32_32x32x16_bf16 v[16:31], v[144:147], v[196:199], v[16:31]
	ds_read_b128 v[248:251], v154 offset:4096
	v_add_f32_e32 v189, v189, v94
	v_add_f32_e32 v165, v165, v188
	v_add_f32_e32 v189, v189, v95
	v_mfma_f32_32x32x16_bf16 v[0:15], v[148:151], v[196:199], v[0:15]
	ds_read_b128 v[204:207], v155 offset:4096
	v_add_f32_e32 v165, v165, v189
	v_max3_f32 v166, v64, v65, v66
	v_max3_f32 v166, v166, v67, v68
	s_waitcnt lgkmcnt(8)
	v_mfma_f32_32x32x16_bf16 v[48:63], v[96:99], v[200:203], v[48:63]
	v_max3_f32 v166, v166, v69, v70
	v_max3_f32 v166, v166, v71, v72
	v_max3_f32 v166, v166, v73, v74
	v_mfma_f32_32x32x16_bf16 v[32:47], v[100:103], v[200:203], v[32:47]
	v_max3_f32 v166, v166, v75, v76
	v_max3_f32 v166, v166, v77, v78
	v_max_f32_e32 v166, v166, v79
	v_cmp_lt_f32_e32 vcc, s92, v166
	s_waitcnt lgkmcnt(4)
	v_mfma_f32_32x32x16_bf16 v[16:31], v[104:107], v[200:203], v[16:31]
	v_mfma_f32_32x32x16_bf16 v[0:15], v[108:111], v[200:203], v[0:15]
	s_cbranch_vccnz .Lda_h4_resc
